# local seams wait only for the 8-workgroup team that owns the same 256-token panel (norm rows remapped to the team's panel)
# speedup vs baseline: 1.0159x; 1.0066x over previous
.LBB0_11:
	v_readlane_b32 s4, v240, 1
	v_readlane_b32 s5, v240, 2
	s_load_dwordx2 s[6:7], s[4:5], 0xe0
	s_load_dwordx8 s[8:15], s[4:5], 0xc0
	v_readlane_b32 s3, v240, 0
	s_mov_b32 s78, s3
	v_mov_b32_e32 v0, v165
	s_waitcnt lgkmcnt(0)
	v_writelane_b32 v239, s8, 21
	v_mbcnt_lo_u32_b32 v0, -1, v0
	v_mbcnt_hi_u32_b32 v211, -1, v0
	v_writelane_b32 v239, s9, 22
	v_writelane_b32 v239, s10, 23
	v_writelane_b32 v239, s11, 24
	v_writelane_b32 v239, s12, 25
	v_writelane_b32 v239, s13, 26
	v_writelane_b32 v239, s14, 27
	v_writelane_b32 v239, s15, 28
	s_load_dwordx16 s[8:23], s[4:5], 0x0
	v_writelane_b32 v239, s6, 29
	v_readlane_b32 s3, v240, 55
	s_cmp_lt_i32 s70, 29
	v_writelane_b32 v239, s7, 30
	s_waitcnt lgkmcnt(0)
	v_writelane_b32 v239, s8, 31
	v_add_u32_e32 v210, s3, v211
	s_mov_b64 s[6:7], -1
	v_writelane_b32 v239, s9, 32
	v_writelane_b32 v239, s10, 33
	v_writelane_b32 v239, s11, 34
	v_writelane_b32 v239, s12, 35
	v_writelane_b32 v239, s13, 36
	v_writelane_b32 v239, s14, 37
	v_writelane_b32 v239, s15, 38
	v_writelane_b32 v239, s16, 39
	v_writelane_b32 v239, s17, 40
	v_writelane_b32 v239, s18, 41
	v_writelane_b32 v239, s19, 42
	v_writelane_b32 v239, s20, 43
	v_writelane_b32 v239, s21, 44
	v_writelane_b32 v239, s22, 45
	v_writelane_b32 v239, s23, 46
	s_load_dwordx16 s[16:31], s[4:5], 0x40
	s_load_dwordx16 s[36:51], s[4:5], 0x80
	s_mov_b64 s[12:13], 0
	s_mov_b64 s[4:5], 0
	s_cbranch_scc1 .LBB0_28
	s_cmp_eq_u32 s70, 29
	s_mov_b64 s[4:5], -1
	s_cbranch_scc0 .LBB0_32
	s_waitcnt lgkmcnt(0)
	v_readlane_b32 s34, v239, 29
	v_readlane_b32 s35, v239, 30
	v_readlane_b32 s14, v239, 25
	v_readlane_b32 s15, v239, 26
	v_and_b32_e32 v8, 63, v211
	v_lshlrev_b32_e32 v0, 5, v8
	v_lshlrev_b32_e32 v1, 4, v8
	v_lshlrev_b32_e32 v9, 2, v8
	v_xor_b32_e32 v2, 0x4, v9
	v_xor_b32_e32 v3, 0x8, v9
	v_xor_b32_e32 v4, 0x10, v9
	v_xor_b32_e32 v5, 0x20, v9
	v_xor_b32_e32 v6, 0x40, v9
	v_xor_b32_e32 v7, 0x80, v9
	v_readlane_b32 s3, v240, 55
	v_readlane_b32 s6, v239, 10
	s_lshr_b32 s3, s3, 6
	s_lshl_b32 s3, s3, 2
	s_and_b32 s7, s78, 7
	s_lshl_b32 s7, s7, 10
	s_add_i32 s3, s3, s7
	s_bfe_u32 s7, s78, 0x20003
	s_lshl_b32 s7, s7, 8
	s_add_i32 s3, s3, s7
	s_lshr_b32 s7, s78, 5
	s_lshl_b32 s7, s7, 5
	s_add_i32 s3, s3, s7
	s_lshl_b32 s6, s6, 3
	s_cmpk_lt_i32 s3, 0x2000
	s_cbranch_scc0 .LnormF_end

.LBB0_82:
	v_readlane_b32 s34, v239, 29
	v_readlane_b32 s35, v239, 30
	s_and_b64 vcc, exec, s[4:5]
	s_cbranch_vccz .LBB0_99
	s_waitcnt lgkmcnt(0)
	s_lshl_b32 s7, s79, 12
	s_add_u32 s18, s18, s7
	s_addc_u32 s19, s19, 0
	v_readlane_b32 s14, v239, 51
	v_readlane_b32 s15, v239, 52
	v_and_b32_e32 v8, 63, v211
	v_lshlrev_b32_e32 v0, 5, v8
	v_lshlrev_b32_e32 v1, 4, v8
	v_lshlrev_b32_e32 v9, 2, v8
	v_xor_b32_e32 v2, 0x4, v9
	v_xor_b32_e32 v3, 0x8, v9
	v_xor_b32_e32 v4, 0x10, v9
	v_xor_b32_e32 v5, 0x20, v9
	v_xor_b32_e32 v6, 0x40, v9
	v_xor_b32_e32 v7, 0x80, v9
	v_readlane_b32 s3, v240, 55
	v_readlane_b32 s6, v239, 10
	s_lshr_b32 s3, s3, 6
	s_lshl_b32 s3, s3, 2
	s_and_b32 s7, s78, 7
	s_lshl_b32 s7, s7, 10
	s_add_i32 s3, s3, s7
	s_bfe_u32 s7, s78, 0x20003
	s_lshl_b32 s7, s7, 8
	s_add_i32 s3, s3, s7
	s_lshr_b32 s7, s78, 5
	s_lshl_b32 s7, s7, 5
	s_add_i32 s3, s3, s7
	s_lshl_b32 s6, s6, 3
	s_cmpk_lt_i32 s3, 0x2000
	s_cbranch_scc0 .Lnorm2_end

.LBB0_293:
	v_readlane_b32 s72, v239, 17
	s_andn2_b64 vcc, exec, s[66:67]
	v_readlane_b32 s73, v239, 18
	s_cbranch_vccnz .LBB0_348
	s_waitcnt lgkmcnt(0)
	v_readlane_b32 s46, v239, 29
	v_readlane_b32 s47, v239, 30
	s_lshl_b32 s7, s79, 12
	s_add_u32 s16, s16, s7
	s_addc_u32 s17, s17, 0
	v_readlane_b32 s14, v239, 51
	v_readlane_b32 s15, v239, 52
	s_add_i32 s3, s70, 5
	s_cmp_lt_u32 s3, 13
	s_cbranch_scc0 .Lnorm1_regular
	v_readlane_b32 s18, v239, 31
	v_readlane_b32 s19, v239, 32
	v_readlane_b32 s34, v239, 33
	v_readlane_b32 s35, v239, 34
	v_and_b32_e32 v8, 63, v211
	v_lshlrev_b32_e32 v0, 5, v8
	v_lshlrev_b32_e32 v1, 4, v8
	v_lshlrev_b32_e32 v9, 2, v8
	v_xor_b32_e32 v2, 0x4, v9
	v_xor_b32_e32 v3, 0x8, v9
	v_xor_b32_e32 v4, 0x10, v9
	v_xor_b32_e32 v5, 0x20, v9
	v_xor_b32_e32 v6, 0x40, v9
	v_xor_b32_e32 v7, 0x80, v9
	v_readlane_b32 s3, v240, 55
	v_readlane_b32 s6, v239, 10
	s_lshr_b32 s3, s3, 6
	s_lshl_b32 s3, s3, 2
	s_and_b32 s7, s78, 7
	s_lshl_b32 s7, s7, 10
	s_add_i32 s3, s3, s7
	s_bfe_u32 s7, s78, 0x20003
	s_lshl_b32 s7, s7, 8
	s_add_i32 s3, s3, s7
	s_lshr_b32 s7, s78, 5
	s_lshl_b32 s7, s7, 5
	s_add_i32 s3, s3, s7
	s_lshl_b32 s6, s6, 3
	s_cmpk_lt_i32 s3, 0x2000
	s_cbranch_scc0 .Lnorm1f_end

.Lnorm1_regular:
	v_and_b32_e32 v8, 63, v211
	v_lshlrev_b32_e32 v0, 5, v8
	v_lshlrev_b32_e32 v1, 4, v8
	v_lshlrev_b32_e32 v9, 2, v8
	v_xor_b32_e32 v2, 0x4, v9
	v_xor_b32_e32 v3, 0x8, v9
	v_xor_b32_e32 v4, 0x10, v9
	v_xor_b32_e32 v5, 0x20, v9
	v_xor_b32_e32 v6, 0x40, v9
	v_xor_b32_e32 v7, 0x80, v9
	v_readlane_b32 s3, v240, 55
	v_readlane_b32 s6, v239, 10
	s_lshr_b32 s3, s3, 6
	s_lshl_b32 s3, s3, 2
	s_and_b32 s7, s78, 7
	s_lshl_b32 s7, s7, 10
	s_add_i32 s3, s3, s7
	s_bfe_u32 s7, s78, 0x20003
	s_lshl_b32 s7, s7, 8
	s_add_i32 s3, s3, s7
	s_lshr_b32 s7, s78, 5
	s_lshl_b32 s7, s7, 5
	s_add_i32 s3, s3, s7
	s_lshl_b32 s6, s6, 3
	s_cmpk_lt_i32 s3, 0x2000
	s_cbranch_scc0 .Lnorm1_end

.Lxb_have:
	v_readfirstlane_b32 s10, v0
	v_readfirstlane_b32 s11, v1
	v_readlane_b32 s8, v240, 60
	s_add_i32 s101, s101, 1
	v_mov_b32_e32 v2, 1
	s_nop 1
	v_mov_b32_e32 v4, s8
	ds_read_b32 v4, v4 offset:8
	v_readlane_b32 s8, v240, 0
	s_nop 0
	s_lshl_b32 s9, s8, 6
	s_add_u32 s9, s9, 0x4000
	s_add_u32 s14, s6, s9
	s_addc_u32 s15, s7, 0
	s_waitcnt lgkmcnt(0)
	v_readfirstlane_b32 s9, v4
	s_cmp_eq_u32 s9, 1
	s_cbranch_scc0 .Lxb_grid
	s_mov_b32 s9, 0x3cfdf3f4
	s_bitcmp1_b32 s9, s70
	s_cbranch_scc0 .Lxb_grid
	s_and_b32 s9, s8, 7
	s_lshl_b32 s9, s9, 8
	s_add_u32 s9, s9, 0x12000
	s_add_u32 s12, s6, s9
	s_addc_u32 s13, s7, 0
	s_lshr_b32 s9, s8, 3
	s_lshl_b32 s9, s9, 2
	v_mov_b32_e32 v3, s9
	v_mov_b32_e32 v2, s101
	global_store_dword v3, v2, s[12:13]
	s_bfe_u32 s9, s8, 0x20003
	s_lshl_b32 s9, s9, 2
	s_mov_b32 exec_lo, 0xff
	s_mov_b32 exec_hi, 0
	v_mbcnt_lo_u32_b32 v3, -1, 0
	v_lshlrev_b32_e32 v3, 4, v3
	v_add_u32_e32 v3, s9, v3
	s_mov_b32 s9, 0
